# prologue x->bf16 pass: 8 consecutive floats per lane per half row, one 16-B store per half row instead of four 8-B stores per row
# baseline (speedup 1.0000x reference)
.LBB0_969:
	v_ashrrev_i32_e32 v0, 6, v182
	v_readlane_b32 s0, v252, 35
	s_waitcnt lgkmcnt(0)
	s_barrier
	v_add_u32_e32 v2, s0, v0
	s_movk_i32 s0, 0x4000
	v_cmp_gt_i32_e32 vcc, s0, v2
	s_and_saveexec_b64 s[0:1], vcc
	s_cbranch_execz .LBB0_974
	v_and_b32_e32 v3, 63, v182
	v_lshlrev_b32_e32 v0, 2, v3
	v_and_b32_e32 v6, 64, v216
	v_add_u32_e32 v8, 64, v6
	v_lshl_add_u64 v[6:7], s[30:31], 0, v[0:1]
	v_xor_b32_e32 v0, 32, v216
	v_cmp_lt_i32_e64 s[38:39], v0, v8
	v_lshlrev_b32_e32 v4, 4, v3
	v_mov_b32_e32 v5, v1
	v_cndmask_b32_e64 v0, v216, v0, s[38:39]
	v_lshlrev_b32_e32 v10, 2, v0
	v_xor_b32_e32 v0, 16, v216
	v_cmp_lt_i32_e64 s[38:39], v0, v8
	v_lshl_add_u64 v[4:5], s[28:29], 0, v[4:5]
	v_cmp_gt_u32_e32 vcc, 16, v3
	v_cndmask_b32_e64 v0, v216, v0, s[38:39]
	v_lshlrev_b32_e32 v11, 2, v0
	v_xor_b32_e32 v0, 8, v216
	v_cmp_lt_i32_e64 s[38:39], v0, v8
	v_cmp_eq_u32_e64 s[36:37], 0, v3
	s_lshl_b32 s8, s12, 3
	v_cndmask_b32_e64 v0, v216, v0, s[38:39]
	v_lshlrev_b32_e32 v12, 2, v0
	v_xor_b32_e32 v0, 4, v216
	v_cmp_lt_i32_e64 s[38:39], v0, v8
	s_mov_b64 s[4:5], 0
	s_nop 0
	v_cndmask_b32_e64 v0, v216, v0, s[38:39]
	v_lshlrev_b32_e32 v13, 2, v0
	v_xor_b32_e32 v0, 2, v216
	v_cmp_lt_i32_e64 s[38:39], v0, v8
	s_nop 1
	v_cndmask_b32_e64 v0, v216, v0, s[38:39]
	v_lshlrev_b32_e32 v14, 2, v0
	v_xor_b32_e32 v0, 1, v216
	v_cmp_lt_i32_e64 s[38:39], v0, v8
	s_nop 1
	v_cndmask_b32_e64 v0, v216, v0, s[38:39]
	v_lshlrev_b32_e32 v15, 2, v0
	v_lshlrev_b32_e32 v0, 5, v3
	v_lshl_add_u64 v[8:9], s[72:73], 0, v[0:1]
	s_branch .LBB0_972

.LBB0_972:
	v_ashrrev_i32_e32 v3, 31, v2
	s_waitcnt lgkmcnt(0)
	v_lshlrev_b64 v[16:17], 12, v[2:3]
	v_lshl_add_u64 v[28:29], v[8:9], 0, v[16:17]
	global_load_dwordx4 v[16:19], v[28:29], off
	global_load_dwordx4 v[20:23], v[28:29], off offset:16
	global_load_dwordx4 v[24:27], v[28:29], off offset:2048
	global_load_dwordx4 v[28:31], v[28:29], off offset:2064
	v_lshlrev_b64 v[32:33], 11, v[2:3]
	v_lshl_add_u64 v[32:33], v[4:5], 0, v[32:33]
	s_waitcnt vmcnt(2)
	v_mul_f32_e32 v0, v17, v17
	v_fmac_f32_e32 v0, v16, v16
	v_fmac_f32_e32 v0, v18, v18
	v_fmac_f32_e32 v0, v19, v19
	v_mul_f32_e32 v34, v21, v21
	v_fmac_f32_e32 v34, v20, v20
	v_fmac_f32_e32 v34, v22, v22
	v_fmac_f32_e32 v34, v23, v23
	v_add_f32_e32 v0, v0, v34
	v_cvt_pk_bf16_f32 v16, v16, v17
	v_cvt_pk_bf16_f32 v17, v18, v19
	v_cvt_pk_bf16_f32 v18, v20, v21
	v_cvt_pk_bf16_f32 v19, v22, v23
	global_store_dwordx4 v[32:33], v[16:19], off
	s_waitcnt vmcnt(1)
	v_mul_f32_e32 v34, v25, v25
	v_fmac_f32_e32 v34, v24, v24
	v_fmac_f32_e32 v34, v26, v26
	v_fmac_f32_e32 v34, v27, v27
	v_add_f32_e32 v0, v0, v34
	v_mul_f32_e32 v34, v29, v29
	v_fmac_f32_e32 v34, v28, v28
	v_fmac_f32_e32 v34, v30, v30
	v_fmac_f32_e32 v34, v31, v31
	v_add_f32_e32 v0, v0, v34
	v_cvt_pk_bf16_f32 v24, v24, v25
	v_cvt_pk_bf16_f32 v25, v26, v27
	v_cvt_pk_bf16_f32 v26, v28, v29
	v_cvt_pk_bf16_f32 v27, v30, v31
	global_store_dwordx4 v[32:33], v[24:27], off offset:1024
	ds_bpermute_b32 v16, v10, v0
	s_waitcnt lgkmcnt(0)
	v_add_f32_e32 v0, v0, v16
	ds_bpermute_b32 v16, v11, v0
	s_waitcnt lgkmcnt(0)
	v_add_f32_e32 v0, v0, v16
	ds_bpermute_b32 v16, v12, v0
	s_waitcnt lgkmcnt(0)
	v_add_f32_e32 v0, v0, v16
	ds_bpermute_b32 v16, v13, v0
	s_waitcnt lgkmcnt(0)
	v_add_f32_e32 v0, v0, v16
	ds_bpermute_b32 v16, v14, v0
	s_waitcnt lgkmcnt(0)
	v_add_f32_e32 v0, v0, v16
	ds_bpermute_b32 v16, v15, v0
	s_and_saveexec_b64 s[6:7], vcc
	s_cbranch_execz .LBB0_971
	s_waitcnt lgkmcnt(0)
	v_add_f32_e32 v0, v0, v16
	v_lshlrev_b64 v[16:17], 6, v[2:3]
	v_cndmask_b32_e64 v0, 0, v0, s[36:37]
	v_lshl_add_u64 v[16:17], v[6:7], 0, v[16:17]
	global_store_dword v[16:17], v0, off
	s_branch .LBB0_971
